# attention online softmax keeps its reference value unless a tile exceeds it by >2^24 (both tile paths): accumulator rescale only on the first tile of a branch
# speedup vs baseline: 1.0140x; 1.0140x over previous
.LBB0_1107:
	s_lshl_b32 s2, 1, s10
	v_and_b32_e32 v0, s2, v205
	v_cmp_ne_u32_e32 vcc, 0, v0
	s_or_b64 s[2:3], s[8:9], vcc
	v_cndmask_b32_e64 v0, 0, 1, s[2:3]
	v_cmp_ne_u32_e32 vcc, 0, v0
	s_cbranch_vccz .LBB0_1118
	s_lshl_b32 s24, s10, 6
	s_cmp_gt_i32 s24, s17
	s_cselect_b64 s[10:11], -1, 0
	s_cmp_eq_u32 s23, 2
	s_cselect_b64 s[12:13], -1, 0
	s_sub_i32 s5, s20, s24
	s_cmpk_gt_i32 s5, 0x1ff
	s_cselect_b64 s[26:27], -1, 0
	s_lshl_b32 s5, s21, 14
	v_add_u32_e32 v32, s5, v206
	ds_read_b128 v[0:3], v32
	ds_read_b128 v[4:7], v32 offset:512
	ds_read_b128 v[8:11], v32 offset:2048
	ds_read_b128 v[12:15], v32 offset:2560
	ds_read_b128 v[16:19], v32 offset:4096
	ds_read_b128 v[20:23], v32 offset:4608
	ds_read_b128 v[24:27], v32 offset:6144
	ds_read_b128 v[28:31], v32 offset:6656
	s_waitcnt lgkmcnt(0)
	v_mfma_f32_32x32x16_bf16 v[114:129], v[0:3], v[130:133], 0
	s_and_b64 s[12:13], s[12:13], s[26:27]
	s_or_b64 s[10:11], s[10:11], s[12:13]
	s_mov_b64 s[12:13], -1
	s_andn2_b64 vcc, exec, s[10:11]
	v_mfma_f32_32x32x16_bf16 v[98:113], v[4:7], v[130:133], 0
	ds_read_b128 v[0:3], v32 offset:8192
	ds_read_b128 v[4:7], v32 offset:8704
	v_mfma_f32_32x32x16_bf16 v[114:129], v[8:11], v[134:137], v[114:129]
	v_mfma_f32_32x32x16_bf16 v[98:113], v[12:15], v[134:137], v[98:113]
	ds_read_b128 v[8:11], v32 offset:10240
	ds_read_b128 v[12:15], v32 offset:10752
	v_mfma_f32_32x32x16_bf16 v[114:129], v[16:19], v[138:141], v[114:129]
	v_mfma_f32_32x32x16_bf16 v[98:113], v[20:23], v[138:141], v[98:113]
	ds_read_b128 v[16:19], v32 offset:12288
	ds_read_b128 v[20:23], v32 offset:12800
	v_mfma_f32_32x32x16_bf16 v[114:129], v[24:27], v[142:145], v[114:129]
	v_mfma_f32_32x32x16_bf16 v[98:113], v[28:31], v[142:145], v[98:113]
	ds_read_b128 v[24:27], v32 offset:14336
	ds_read_b128 v[28:31], v32 offset:14848
	s_waitcnt lgkmcnt(0)
	v_mfma_f32_32x32x16_bf16 v[114:129], v[0:3], v[146:149], v[114:129]
	v_mfma_f32_32x32x16_bf16 v[98:113], v[4:7], v[146:149], v[98:113]
	v_mfma_f32_32x32x16_bf16 v[114:129], v[8:11], v[150:153], v[114:129]
	v_mfma_f32_32x32x16_bf16 v[98:113], v[12:15], v[150:153], v[98:113]
	v_mfma_f32_32x32x16_bf16 v[114:129], v[16:19], v[154:157], v[114:129]
	v_mfma_f32_32x32x16_bf16 v[98:113], v[20:23], v[154:157], v[98:113]
	v_mfma_f32_32x32x16_bf16 v[114:129], v[24:27], v[158:161], v[114:129]
	v_mfma_f32_32x32x16_bf16 v[98:113], v[28:31], v[158:161], v[98:113]
	s_cbranch_vccz .LBB0_1116
	s_nop 9
	v_max3_f32 v0, v114, s94, v115
	v_max3_f32 v0, v0, v116, v117
	v_max3_f32 v0, v0, v118, v119
	v_max3_f32 v0, v0, v120, v121
	v_max3_f32 v0, v0, v122, v123
	v_max3_f32 v0, v0, v124, v125
	v_max3_f32 v0, v0, v126, v127
	v_max3_f32 v0, v0, v128, v129
	v_max3_f32 v0, v0, v98, v99
	v_max3_f32 v0, v0, v100, v101
	v_max3_f32 v0, v0, v102, v103
	v_max3_f32 v0, v0, v104, v105
	v_max3_f32 v0, v0, v106, v107
	v_max3_f32 v0, v0, v108, v109
	v_max3_f32 v0, v0, v110, v111
	v_max3_f32 v0, v0, v112, v113
	ds_bpermute_b32 v1, v168, v0
	v_cndmask_b32_e64 v2, v233, v204, s[2:3]
	v_max_f32_e32 v3, v209, v209
	s_waitcnt lgkmcnt(0)
	v_max_f32_e32 v1, v1, v1
	v_max_f32_e32 v0, v0, v1
	v_add_f32_e32 v0, v2, v0
	v_max_f32_e32 v210, v3, v0
	v_sub_f32_e32 v1, v210, v3
	v_cmp_lt_f32_e32 vcc, 0x41c00000, v1
	v_cndmask_b32_e32 v210, v3, v210, vcc
	v_sub_f32_e32 v167, v2, v210
	v_add_f32_e32 v0, v114, v167
	v_add_f32_e32 v1, v115, v167
	v_exp_f32_e32 v0, v0
	v_exp_f32_e32 v1, v1
	v_add_f32_e32 v2, v116, v167
	v_exp_f32_e32 v2, v2
	v_add_f32_e32 v3, v117, v167
	v_exp_f32_e32 v3, v3
	v_add_f32_e32 v4, 0, v0
	v_add_f32_e32 v4, v1, v4
	v_add_f32_e32 v4, v2, v4
	v_add_f32_e32 v8, v3, v4
	v_add_f32_e32 v4, v118, v167
	v_exp_f32_e32 v4, v4
	v_add_f32_e32 v5, v119, v167
	v_exp_f32_e32 v5, v5
	v_add_f32_e32 v6, v120, v167
	v_exp_f32_e32 v6, v6
	v_add_f32_e32 v7, v121, v167
	v_exp_f32_e32 v7, v7
	v_add_f32_e32 v8, v4, v8
	v_add_f32_e32 v8, v5, v8
	v_add_f32_e32 v8, v6, v8
	v_add_f32_e32 v12, v7, v8
	v_add_f32_e32 v8, v122, v167
	v_exp_f32_e32 v8, v8
	v_add_f32_e32 v9, v123, v167
	v_exp_f32_e32 v9, v9
	v_add_f32_e32 v10, v124, v167
	v_exp_f32_e32 v10, v10
	v_add_f32_e32 v11, v125, v167
	v_exp_f32_e32 v11, v11
	v_add_f32_e32 v12, v8, v12
	v_add_f32_e32 v12, v9, v12
	v_add_f32_e32 v12, v10, v12
	v_add_f32_e32 v16, v11, v12
	v_add_f32_e32 v12, v126, v167
	v_exp_f32_e32 v12, v12
	v_add_f32_e32 v13, v127, v167
	v_exp_f32_e32 v13, v13
	v_add_f32_e32 v14, v128, v167
	v_exp_f32_e32 v14, v14
	v_add_f32_e32 v15, v129, v167
	v_exp_f32_e32 v15, v15
	v_add_f32_e32 v16, v12, v16
	v_add_f32_e32 v16, v13, v16
	v_add_f32_e32 v16, v14, v16
	v_add_f32_e32 v20, v15, v16
	v_add_f32_e32 v16, v98, v167
	v_exp_f32_e32 v16, v16
	v_add_f32_e32 v17, v99, v167
	v_exp_f32_e32 v17, v17
	v_add_f32_e32 v18, v100, v167
	v_exp_f32_e32 v18, v18
	v_add_f32_e32 v19, v101, v167
	v_exp_f32_e32 v19, v19
	v_add_f32_e32 v20, v16, v20
	v_add_f32_e32 v20, v17, v20
	v_add_f32_e32 v20, v18, v20
	v_add_f32_e32 v24, v19, v20
	v_add_f32_e32 v20, v102, v167
	v_exp_f32_e32 v20, v20
	v_add_f32_e32 v21, v103, v167
	v_exp_f32_e32 v21, v21
	v_add_f32_e32 v22, v104, v167
	v_exp_f32_e32 v22, v22
	v_add_f32_e32 v23, v105, v167
	v_exp_f32_e32 v23, v23
	v_add_f32_e32 v24, v20, v24
	v_add_f32_e32 v24, v21, v24
	v_add_f32_e32 v24, v22, v24
	v_add_f32_e32 v28, v23, v24
	v_add_f32_e32 v24, v106, v167
	v_exp_f32_e32 v24, v24
	v_add_f32_e32 v25, v107, v167
	v_exp_f32_e32 v25, v25
	v_add_f32_e32 v26, v108, v167
	v_exp_f32_e32 v26, v26
	v_add_f32_e32 v27, v109, v167
	v_exp_f32_e32 v27, v27
	v_add_f32_e32 v28, v24, v28
	v_add_f32_e32 v28, v25, v28
	v_add_f32_e32 v28, v26, v28
	v_add_f32_e32 v31, v27, v28
	v_add_f32_e32 v28, v110, v167
	v_exp_f32_e32 v28, v28
	v_add_f32_e32 v29, v111, v167
	v_exp_f32_e32 v29, v29
	v_add_f32_e32 v30, v112, v167
	v_exp_f32_e32 v30, v30
	v_add_f32_e32 v31, v28, v31
	v_add_f32_e32 v166, v29, v31
	v_mov_b32_e32 v31, v113
	v_pk_add_f32 v[166:167], v[30:31], v[166:167]
	s_cbranch_execz .LBB0_1117

.LBB0_1117:
	s_and_b64 s[10:11], exec, s[8:9]
	s_brev_b32 s10, -2
	s_cselect_b32 s10, 0x200, s10
	s_or_b32 s11, s24, 2
	v_subrev_u32_e32 v4, s11, v207
	s_or_b32 s11, s24, 3
	v_subrev_u32_e32 v6, s11, v207
	s_or_b32 s11, s24, 4
	v_subrev_u32_e32 v8, s11, v207
	s_or_b32 s11, s24, 5
	v_subrev_u32_e32 v10, s11, v207
	s_or_b32 s11, s24, 6
	v_subrev_u32_e32 v12, s11, v207
	s_or_b32 s11, s24, 7
	v_subrev_u32_e32 v14, s11, v207
	s_or_b32 s11, s24, 16
	v_subrev_u32_e32 v16, s11, v207
	s_or_b32 s11, s24, 17
	v_subrev_u32_e32 v18, s11, v207
	s_or_b32 s11, s24, 18
	v_subrev_u32_e32 v20, s11, v207
	s_or_b32 s11, s24, 19
	v_subrev_u32_e32 v22, s11, v207
	s_or_b32 s11, s24, 20
	v_subrev_u32_e32 v24, s11, v207
	s_or_b32 s11, s24, 21
	v_subrev_u32_e32 v26, s11, v207
	s_or_b32 s11, s24, 22
	v_subrev_u32_e32 v28, s11, v207
	s_or_b32 s11, s24, 23
	v_subrev_u32_e32 v0, s24, v207
	v_xad_u32 v2, s24, -1, v207
	v_subrev_u32_e32 v30, s11, v207
	v_med3_i32 v1, v0, 0, v234
	v_med3_i32 v3, v2, 0, v234
	v_med3_i32 v5, v4, 0, v234
	v_med3_i32 v7, v6, 0, v234
	v_med3_i32 v9, v8, 0, v234
	v_med3_i32 v11, v10, 0, v234
	v_med3_i32 v13, v12, 0, v234
	v_med3_i32 v15, v14, 0, v234
	v_med3_i32 v17, v16, 0, v234
	v_med3_i32 v19, v18, 0, v234
	v_med3_i32 v21, v20, 0, v234
	v_med3_i32 v23, v22, 0, v234
	v_med3_i32 v25, v24, 0, v234
	v_med3_i32 v27, v26, 0, v234
	v_med3_i32 v29, v28, 0, v234
	v_med3_i32 v31, v30, 0, v234
	v_lshl_add_u32 v1, v1, 2, s86
	v_lshl_add_u32 v3, v3, 2, s86
	v_lshl_add_u32 v5, v5, 2, s86
	v_lshl_add_u32 v7, v7, 2, s86
	v_lshl_add_u32 v9, v9, 2, s86
	v_lshl_add_u32 v11, v11, 2, s86
	v_lshl_add_u32 v13, v13, 2, s86
	v_lshl_add_u32 v15, v15, 2, s86
	v_lshl_add_u32 v17, v17, 2, s86
	v_lshl_add_u32 v19, v19, 2, s86
	v_lshl_add_u32 v21, v21, 2, s86
	v_lshl_add_u32 v23, v23, 2, s86
	v_lshl_add_u32 v25, v25, 2, s86
	v_lshl_add_u32 v27, v27, 2, s86
	v_lshl_add_u32 v29, v29, 2, s86
	v_lshl_add_u32 v31, v31, 2, s86
	ds_read_b32 v1, v1
	ds_read_b32 v3, v3
	ds_read_b32 v5, v5
	ds_read_b32 v7, v7
	ds_read_b32 v9, v9
	ds_read_b32 v11, v11
	ds_read_b32 v13, v13
	ds_read_b32 v15, v15
	ds_read_b32 v17, v17
	ds_read_b32 v19, v19
	ds_read_b32 v21, v21
	ds_read_b32 v23, v23
	ds_read_b32 v25, v25
	ds_read_b32 v27, v27
	ds_read_b32 v29, v29
	ds_read_b32 v31, v31
	s_waitcnt lgkmcnt(0)
	v_cmp_gt_u32_e32 vcc, s10, v0
	v_add_f32_e32 v1, v114, v1
	s_and_b64 vcc, s[2:3], vcc
	v_cndmask_b32_e32 v1, v233, v1, vcc
	v_cmp_gt_u32_e32 vcc, s10, v2
	v_add_f32_e32 v3, v115, v3
	s_and_b64 vcc, s[2:3], vcc
	v_cndmask_b32_e32 v3, v233, v3, vcc
	v_cmp_gt_u32_e32 vcc, s10, v4
	v_add_f32_e32 v5, v116, v5
	s_and_b64 vcc, s[2:3], vcc
	v_cndmask_b32_e32 v5, v233, v5, vcc
	v_cmp_gt_u32_e32 vcc, s10, v6
	v_add_f32_e32 v7, v117, v7
	s_and_b64 vcc, s[2:3], vcc
	v_cndmask_b32_e32 v7, v233, v7, vcc
	v_cmp_gt_u32_e32 vcc, s10, v8
	v_add_f32_e32 v9, v118, v9
	s_and_b64 vcc, s[2:3], vcc
	v_cndmask_b32_e32 v9, v233, v9, vcc
	v_cmp_gt_u32_e32 vcc, s10, v10
	v_add_f32_e32 v11, v119, v11
	s_and_b64 vcc, s[2:3], vcc
	v_cndmask_b32_e32 v11, v233, v11, vcc
	v_cmp_gt_u32_e32 vcc, s10, v12
	v_add_f32_e32 v13, v120, v13
	s_and_b64 vcc, s[2:3], vcc
	v_cndmask_b32_e32 v13, v233, v13, vcc
	v_cmp_gt_u32_e32 vcc, s10, v14
	v_add_f32_e32 v15, v121, v15
	s_and_b64 vcc, s[2:3], vcc
	v_cndmask_b32_e32 v15, v233, v15, vcc
	v_cmp_gt_u32_e32 vcc, s10, v16
	v_add_f32_e32 v17, v122, v17
	s_and_b64 vcc, s[2:3], vcc
	v_cndmask_b32_e32 v17, v233, v17, vcc
	v_cmp_gt_u32_e32 vcc, s10, v18
	v_add_f32_e32 v19, v123, v19
	s_and_b64 vcc, s[2:3], vcc
	v_cndmask_b32_e32 v19, v233, v19, vcc
	v_cmp_gt_u32_e32 vcc, s10, v20
	v_add_f32_e32 v21, v124, v21
	s_and_b64 vcc, s[2:3], vcc
	v_cndmask_b32_e32 v21, v233, v21, vcc
	v_cmp_gt_u32_e32 vcc, s10, v22
	v_add_f32_e32 v23, v125, v23
	s_and_b64 vcc, s[2:3], vcc
	v_cndmask_b32_e32 v23, v233, v23, vcc
	v_cmp_gt_u32_e32 vcc, s10, v24
	v_add_f32_e32 v25, v126, v25
	s_and_b64 vcc, s[2:3], vcc
	v_cndmask_b32_e32 v25, v233, v25, vcc
	v_cmp_gt_u32_e32 vcc, s10, v26
	v_add_f32_e32 v27, v127, v27
	s_and_b64 vcc, s[2:3], vcc
	v_cndmask_b32_e32 v27, v233, v27, vcc
	v_cmp_gt_u32_e32 vcc, s10, v28
	v_add_f32_e32 v29, v128, v29
	s_and_b64 vcc, s[2:3], vcc
	v_cndmask_b32_e32 v29, v233, v29, vcc
	v_cmp_gt_u32_e32 vcc, s10, v30
	v_subrev_u32_e32 v0, 32, v0
	v_subrev_u32_e32 v2, 32, v2
	v_subrev_u32_e32 v4, 32, v4
	v_subrev_u32_e32 v6, 32, v6
	v_subrev_u32_e32 v8, 32, v8
	v_subrev_u32_e32 v10, 32, v10
	v_subrev_u32_e32 v12, 32, v12
	v_subrev_u32_e32 v14, 32, v14
	v_subrev_u32_e32 v16, 32, v16
	v_subrev_u32_e32 v18, 32, v18
	v_subrev_u32_e32 v20, 32, v20
	v_subrev_u32_e32 v22, 32, v22
	v_subrev_u32_e32 v24, 32, v24
	v_subrev_u32_e32 v26, 32, v26
	v_subrev_u32_e32 v28, 32, v28
	v_subrev_u32_e32 v30, 32, v30
	v_max3_f32 v32, v1, s94, v3
	v_add_f32_e32 v31, v129, v31
	v_med3_i32 v114, v0, 0, v234
	v_med3_i32 v115, v2, 0, v234
	v_med3_i32 v116, v4, 0, v234
	v_med3_i32 v117, v6, 0, v234
	v_med3_i32 v118, v8, 0, v234
	v_med3_i32 v119, v10, 0, v234
	v_med3_i32 v120, v12, 0, v234
	v_med3_i32 v121, v14, 0, v234
	v_med3_i32 v122, v16, 0, v234
	v_med3_i32 v123, v18, 0, v234
	v_med3_i32 v124, v20, 0, v234
	v_med3_i32 v125, v22, 0, v234
	v_med3_i32 v126, v24, 0, v234
	v_med3_i32 v127, v26, 0, v234
	v_med3_i32 v128, v28, 0, v234
	v_med3_i32 v129, v30, 0, v234
	v_max3_f32 v32, v32, v5, v7
	s_and_b64 vcc, s[2:3], vcc
	v_lshl_add_u32 v114, v114, 2, s86
	v_lshl_add_u32 v115, v115, 2, s86
	v_lshl_add_u32 v116, v116, 2, s86
	v_lshl_add_u32 v117, v117, 2, s86
	v_lshl_add_u32 v118, v118, 2, s86
	v_lshl_add_u32 v119, v119, 2, s86
	v_lshl_add_u32 v120, v120, 2, s86
	v_lshl_add_u32 v121, v121, 2, s86
	v_lshl_add_u32 v122, v122, 2, s86
	v_lshl_add_u32 v123, v123, 2, s86
	v_lshl_add_u32 v124, v124, 2, s86
	v_lshl_add_u32 v125, v125, 2, s86
	v_lshl_add_u32 v126, v126, 2, s86
	v_lshl_add_u32 v127, v127, 2, s86
	v_lshl_add_u32 v128, v128, 2, s86
	v_lshl_add_u32 v129, v129, 2, s86
	v_max3_f32 v32, v32, v9, v11
	v_cndmask_b32_e32 v31, v233, v31, vcc
	ds_read_b32 v114, v114
	ds_read_b32 v115, v115
	ds_read_b32 v116, v116
	ds_read_b32 v117, v117
	ds_read_b32 v118, v118
	ds_read_b32 v119, v119
	ds_read_b32 v120, v120
	ds_read_b32 v121, v121
	ds_read_b32 v122, v122
	ds_read_b32 v123, v123
	ds_read_b32 v124, v124
	ds_read_b32 v125, v125
	ds_read_b32 v126, v126
	ds_read_b32 v127, v127
	ds_read_b32 v128, v128
	ds_read_b32 v129, v129
	v_cmp_gt_u32_e32 vcc, s10, v0
	v_max3_f32 v32, v32, v13, v15
	s_waitcnt lgkmcnt(0)
	s_and_b64 vcc, s[2:3], vcc
	v_add_f32_e32 v0, v98, v114
	v_max3_f32 v32, v32, v17, v19
	v_cndmask_b32_e32 v98, v233, v0, vcc
	v_cmp_gt_u32_e32 vcc, s10, v2
	v_max3_f32 v32, v32, v21, v23
	s_and_b64 vcc, s[2:3], vcc
	v_add_f32_e32 v0, v99, v115
	v_max3_f32 v32, v32, v25, v27
	v_cndmask_b32_e32 v99, v233, v0, vcc
	v_cmp_gt_u32_e32 vcc, s10, v4
	v_max3_f32 v32, v32, v29, v31
	s_and_b64 vcc, s[2:3], vcc
	v_add_f32_e32 v2, v100, v116
	v_max3_f32 v0, v32, v98, v99
	v_cndmask_b32_e32 v32, v233, v2, vcc
	v_cmp_gt_u32_e32 vcc, s10, v6
	s_and_b64 vcc, s[2:3], vcc
	v_add_f32_e32 v2, v101, v117
	v_cndmask_b32_e32 v100, v233, v2, vcc
	v_cmp_gt_u32_e32 vcc, s10, v8
	s_and_b64 vcc, s[2:3], vcc
	v_add_f32_e32 v2, v102, v118
	v_cndmask_b32_e32 v101, v233, v2, vcc
	v_cmp_gt_u32_e32 vcc, s10, v10
	s_and_b64 vcc, s[2:3], vcc
	v_add_f32_e32 v2, v103, v119
	v_cndmask_b32_e32 v102, v233, v2, vcc
	v_cmp_gt_u32_e32 vcc, s10, v12
	s_and_b64 vcc, s[2:3], vcc
	v_add_f32_e32 v2, v104, v120
	v_cndmask_b32_e32 v103, v233, v2, vcc
	v_cmp_gt_u32_e32 vcc, s10, v14
	s_and_b64 vcc, s[2:3], vcc
	v_add_f32_e32 v2, v105, v121
	v_cndmask_b32_e32 v104, v233, v2, vcc
	v_cmp_gt_u32_e32 vcc, s10, v16
	s_and_b64 vcc, s[2:3], vcc
	v_add_f32_e32 v2, v106, v122
	v_cndmask_b32_e32 v105, v233, v2, vcc
	v_cmp_gt_u32_e32 vcc, s10, v18
	s_and_b64 vcc, s[2:3], vcc
	v_add_f32_e32 v2, v107, v123
	v_cndmask_b32_e32 v106, v233, v2, vcc
	v_cmp_gt_u32_e32 vcc, s10, v20
	s_and_b64 vcc, s[2:3], vcc
	v_add_f32_e32 v2, v108, v124
	v_cndmask_b32_e32 v107, v233, v2, vcc
	v_cmp_gt_u32_e32 vcc, s10, v22
	s_and_b64 vcc, s[2:3], vcc
	v_add_f32_e32 v2, v109, v125
	v_cndmask_b32_e32 v108, v233, v2, vcc
	v_cmp_gt_u32_e32 vcc, s10, v24
	s_and_b64 vcc, s[2:3], vcc
	v_add_f32_e32 v2, v110, v126
	v_cndmask_b32_e32 v109, v233, v2, vcc
	v_cmp_gt_u32_e32 vcc, s10, v26
	v_max3_f32 v0, v0, v32, v100
	v_add_f32_e32 v2, v111, v127
	s_and_b64 vcc, s[2:3], vcc
	v_max3_f32 v0, v0, v101, v102
	v_cndmask_b32_e32 v110, v233, v2, vcc
	v_cmp_gt_u32_e32 vcc, s10, v28
	v_max3_f32 v0, v0, v103, v104
	v_add_f32_e32 v2, v112, v128
	s_and_b64 vcc, s[2:3], vcc
	v_max3_f32 v0, v0, v105, v106
	v_cndmask_b32_e32 v111, v233, v2, vcc
	v_cmp_gt_u32_e32 vcc, s10, v30
	v_max3_f32 v0, v0, v107, v108
	v_add_f32_e32 v2, v113, v129
	s_and_b64 vcc, s[2:3], vcc
	v_max3_f32 v0, v0, v109, v110
	v_cndmask_b32_e32 v112, v233, v2, vcc
	v_max3_f32 v0, v0, v111, v112
	ds_bpermute_b32 v2, v168, v0
	s_waitcnt lgkmcnt(0)
	v_max3_f32 v210, v209, v0, v2
	v_sub_f32_e32 v0, v210, v209
	v_cmp_lt_f32_e32 vcc, 0x41c00000, v0
	v_cndmask_b32_e32 v210, v209, v210, vcc
	v_sub_f32_e32 v0, v1, v210
	v_exp_f32_e32 v0, v0
	v_sub_f32_e32 v1, v3, v210
	v_exp_f32_e32 v1, v1
	v_sub_f32_e32 v2, v5, v210
	v_exp_f32_e32 v2, v2
	v_add_f32_e32 v3, 0, v0
	v_add_f32_e32 v3, v1, v3
	v_sub_f32_e32 v4, v9, v210
	v_add_f32_e32 v8, v2, v3
	v_sub_f32_e32 v3, v7, v210
	v_exp_f32_e32 v3, v3
	v_exp_f32_e32 v4, v4
	v_sub_f32_e32 v5, v11, v210
	v_exp_f32_e32 v5, v5
	v_sub_f32_e32 v6, v13, v210
	v_exp_f32_e32 v6, v6
	v_add_f32_e32 v7, v3, v8
	v_add_f32_e32 v7, v4, v7
	v_add_f32_e32 v7, v5, v7
	v_add_f32_e32 v11, v6, v7
	v_sub_f32_e32 v7, v15, v210
	v_exp_f32_e32 v7, v7
	v_sub_f32_e32 v8, v17, v210
	v_exp_f32_e32 v8, v8
	v_sub_f32_e32 v9, v19, v210
	v_exp_f32_e32 v9, v9
	v_sub_f32_e32 v10, v21, v210
	v_exp_f32_e32 v10, v10
	v_add_f32_e32 v11, v7, v11
	v_add_f32_e32 v11, v8, v11
	v_add_f32_e32 v11, v9, v11
	v_add_f32_e32 v15, v10, v11
	v_sub_f32_e32 v11, v23, v210
	v_exp_f32_e32 v11, v11
	v_sub_f32_e32 v12, v25, v210
	v_exp_f32_e32 v12, v12
	v_sub_f32_e32 v13, v27, v210
	v_exp_f32_e32 v13, v13
	v_sub_f32_e32 v14, v29, v210
	v_exp_f32_e32 v14, v14
	v_add_f32_e32 v15, v11, v15
	v_add_f32_e32 v15, v12, v15
	v_add_f32_e32 v15, v13, v15
	v_add_f32_e32 v19, v14, v15
	v_sub_f32_e32 v15, v31, v210
	v_exp_f32_e32 v15, v15
	v_sub_f32_e32 v16, v98, v210
	v_exp_f32_e32 v16, v16
	v_sub_f32_e32 v17, v99, v210
	v_exp_f32_e32 v17, v17
	v_sub_f32_e32 v18, v32, v210
	v_exp_f32_e32 v18, v18
	v_add_f32_e32 v19, v15, v19
	v_add_f32_e32 v19, v16, v19
	v_add_f32_e32 v19, v17, v19
	v_add_f32_e32 v23, v18, v19
	v_sub_f32_e32 v19, v100, v210
	v_exp_f32_e32 v19, v19
	v_sub_f32_e32 v20, v101, v210
	v_exp_f32_e32 v20, v20
	v_sub_f32_e32 v21, v102, v210
	v_exp_f32_e32 v21, v21
	v_sub_f32_e32 v22, v103, v210
	v_exp_f32_e32 v22, v22
	v_add_f32_e32 v23, v19, v23
	v_add_f32_e32 v23, v20, v23
	v_add_f32_e32 v23, v21, v23
	v_add_f32_e32 v27, v22, v23
	v_sub_f32_e32 v23, v104, v210
	v_exp_f32_e32 v23, v23
	v_sub_f32_e32 v24, v105, v210
	v_exp_f32_e32 v24, v24
	v_sub_f32_e32 v25, v106, v210
	v_exp_f32_e32 v25, v25
	v_sub_f32_e32 v26, v107, v210
	v_exp_f32_e32 v26, v26
	v_add_f32_e32 v27, v23, v27
	v_add_f32_e32 v27, v24, v27
	v_add_f32_e32 v27, v25, v27
	v_add_f32_e32 v31, v26, v27
	v_sub_f32_e32 v27, v108, v210
	v_exp_f32_e32 v27, v27
	v_sub_f32_e32 v28, v109, v210
	v_exp_f32_e32 v28, v28
	v_sub_f32_e32 v29, v110, v210
	v_exp_f32_e32 v29, v29
	v_sub_f32_e32 v30, v111, v210
	v_exp_f32_e32 v30, v30
	v_add_f32_e32 v31, v27, v31
	v_add_f32_e32 v31, v28, v31
	v_add_f32_e32 v31, v29, v31
	v_add_f32_e32 v166, v30, v31
	v_sub_f32_e32 v167, v112, v210
	v_sub_f32_e32 v31, v209, v210
	v_exp_f32_e32 v32, v31
	s_nop 0
	v_cmp_neq_f32_e32 vcc, 1.0, v32
	s_cbranch_vccnz .LBB0_1111
	s_branch .LBB0_1112
